# attention job prologues (sparse and both dilated-window variants): q fragments, first K/V tile DMA and first mask words issued before the bias-LUT wait, one memory round trip instead of two
# speedup vs baseline: 1.0292x; 1.0032x over previous
; #define LAS __attribute__((address_space(3)))
; DI void load_lut(float* lut, const float* glut, int col, int lane) {
;     ...
;     for (int k = 0; k < 8; ++k) t[k] = *(const f32x4*)(glut + (size_t)col * 2048 + k * 256 + lane * 4);
; #pragma unroll
;     for (int k = 0; k < 8; ++k) *(f32x4*)(lut + k * 256 + lane * 4) = t[k];
;     __builtin_amdgcn_fence(__ATOMIC_ACQ_REL, "wavefront");
;     __builtin_amdgcn_wave_barrier();
; }
; DI void attn_job(const Args& a, unsigned char* wsh, LAS unsigned char* wl, int type, int b, int qt, int hd, const int tid) {
;     const int lane = tid & 63, r = lane & 31, h = lane >> 5;
;     const bf16_t* prm = (const bf16_t*)(a.ws + WS_R1);
;     const bf16_t* prt = prm + (size_t)MTOK * RM_LD;
;     const float* glut = (const float*)(a.ws + WS_LUT);
;     const unsigned* mask = (const unsigned*)(a.ws + WS_MASK);
;     const float* kmean = (const float*)(a.ws + WS_KMEAN);
;     bf16_t* oabc = (bf16_t*)(a.ws + WS_OABC);
;     float* lut = (float*)(wsh + 8192);
;     const int t0 = qt * 32, tok0 = b * SEQ;
;     const int d00 = t0 + r - 8 * h, h8 = 8 * h;
;     const unsigned* maskrow = mask + (size_t)(tok0 + t0 + r) * 64;
;     AttnCtx c; c.wl = wl; c.lut = lut; c.krs = 1;
; #pragma unroll
;     for (int j = 0; j < 4; ++j) {
;         const int rk = 8 * j + (lane >> 3), ck = (lane & 7) ^ ((rk >> 1) & 7);
;         c.koff[j] = (unsigned)(pi_row(rk) * RM_LD + ck * 8) * 2u;
;         const int rv = 16 * j + (lane >> 2), cv = (lane & 3) ^ ((rv >> 2) & 3);
;         c.voff[j] = (unsigned)(rv * MTOK + cv * 8) * 2u;
;         c.kfo[j] = r * 128 + (((2 * j + h) ^ ((r >> 1) & 7)) * 16);
;     }
; #pragma unroll
;     for (int mt = 0; mt < 2; ++mt)
; #pragma unroll
;         for (int s = 0; s < 2; ++s) c.vfo[mt][s] = (32 * mt + r) * 64 + (((2 * s + h) ^ ((r >> 2) & 3)) * 16);
;     AttnSt st; st.m = NEGF; st.l = 0.f;
; #pragma unroll
;     for (int i = 0; i < 16; ++i) { st.o0[i] = 0.f; st.o1[i] = 0.f; }
;     const int ng = (type == 1) ? 2 : 1;
;     int ocol = 0;
;     for (int g = 0; g < ng; ++g) {
;         int qcol, kcol, vrow, bcol;
;         if (type == 0) { qcol = C_AQ + hd * 64; kcol = C_AK; vrow = R_AV; bcol = hd; ocol = hd * 64; }
;         else if (type == 1) { qcol = C_BQ + (g * 4 + hd) * 64; kcol = C_BK + hd * 64; vrow = R_BV + hd * 64; bcol = 6 + g * 4 + hd; ocol = 384 + hd * 64; }
.LBB0_281:
	s_add_i32 s2, s8, s58
	s_lshl_b32 s2, s2, 11
	v_lshl_add_u64 v[50:51], s[2:3], 2, v[130:131]
	v_add_co_u32_e32 v62, vcc, s94, v50
	s_nop 1
	v_addc_co_u32_e32 v63, vcc, 0, v51, vcc
	global_load_dwordx4 v[34:37], v[50:51], off
	global_load_dwordx4 v[38:41], v[50:51], off offset:1024
	global_load_dwordx4 v[42:45], v[50:51], off offset:2048
	global_load_dwordx4 v[46:49], v[50:51], off offset:3072
	s_nop 0
	global_load_dwordx4 v[50:53], v[62:63], off
	global_load_dwordx4 v[54:57], v[62:63], off offset:1024
	global_load_dwordx4 v[58:61], v[62:63], off offset:2048
	s_nop 0
	global_load_dwordx4 v[62:65], v[62:63], off offset:3072
	s_xor_b64 s[4:5], s[6:7], -1
	s_and_b64 s[6:7], s[6:7], exec
	s_cselect_b32 s2, 0xffffff80, s73
	s_add_i32 s2, s2, s60
	s_max_i32 s6, s2, 0
	s_lshr_b32 s69, s6, 5
	s_cmp_gt_i32 s69, s57
	s_cbranch_scc1 .Lnoh_B
	s_add_i32 s2, s8, s0
	s_lshl_b32 s2, s2, 7
	s_mul_i32 s7, s6, 0x1600
	v_lshl_add_u64 v[82:83], v[146:147], 0, s[2:3]
	s_mul_hi_u32 s2, s6, 0x1600
	s_add_u32 s8, s1, s7
	s_addc_u32 s9, s66, s2
	global_load_dwordx4 v[66:69], v[82:83], off offset:2144
	global_load_dwordx4 v[70:73], v[82:83], off offset:2112
	global_load_dwordx4 v[74:77], v[82:83], off offset:2080
	global_load_dwordx4 v[78:81], v[82:83], off offset:2048
	v_lshl_add_u64 v[82:83], s[8:9], 0, v[116:117]
	s_mov_b32 m0, s49
	v_lshl_add_u64 v[82:83], v[82:83], 0, s[20:21]
	global_load_lds_dwordx4 v[82:83], off
	v_lshl_add_u64 v[82:83], s[8:9], 0, v[118:119]
	s_add_i32 s2, s49, 0x400
	v_lshl_add_u64 v[82:83], v[82:83], 0, s[20:21]
	s_mov_b32 m0, s2
	s_add_i32 s70, s49, 0x800
	global_load_lds_dwordx4 v[82:83], off
	v_lshl_add_u64 v[82:83], s[8:9], 0, v[122:123]
	v_lshl_add_u64 v[82:83], v[82:83], 0, s[20:21]
	s_mov_b32 m0, s70
	s_lshl_b32 s7, s6, 1
	global_load_lds_dwordx4 v[82:83], off
	v_lshl_add_u64 v[82:83], s[8:9], 0, v[126:127]
	s_add_u32 s8, s67, s7
	v_lshl_add_u64 v[82:83], v[82:83], 0, s[20:21]
	s_mov_b32 m0, s53
	s_addc_u32 s9, s68, 0
	s_add_i32 s71, s49, 0x1000
	global_load_lds_dwordx4 v[82:83], off
	v_lshl_add_u64 v[82:83], s[8:9], 0, v[114:115]
	s_mov_b32 m0, s71
	s_add_i32 s72, s49, 0x1800
	global_load_lds_dwordx4 v[82:83], off
	v_lshl_add_u64 v[82:83], s[8:9], 0, v[120:121]
	s_mov_b32 m0, s54
	s_nop 0
	global_load_lds_dwordx4 v[82:83], off
	v_lshl_add_u64 v[82:83], s[8:9], 0, v[124:125]
	s_mov_b32 m0, s72
	s_nop 0
	global_load_lds_dwordx4 v[82:83], off
	v_lshl_add_u64 v[82:83], s[8:9], 0, v[128:129]
	s_mov_b32 m0, s55
	s_nop 0
	global_load_lds_dwordx4 v[82:83], off
.Lnoh_B:
	s_waitcnt vmcnt(0)
	ds_write_b128 v143, v[34:37] offset:8192
	ds_write_b128 v143, v[38:41] offset:9216
	ds_write_b128 v143, v[42:45] offset:10240
	ds_write_b128 v143, v[46:49] offset:11264
	ds_write_b128 v143, v[50:53] offset:12288
	ds_write_b128 v143, v[54:57] offset:13312
	ds_write_b128 v143, v[58:61] offset:14336
	ds_write_b128 v143, v[62:65] offset:15360
	s_cmp_gt_i32 s69, s57
	s_cbranch_scc1 .LBB0_296
	v_subrev_u32_e32 v0, s6, v166
	v_lshl_add_u32 v0, v0, 2, s51
	v_subrev_u32_e32 v151, s6, v167
	v_subrev_u32_e32 v34, s6, v168
	v_lshl_add_u32 v152, v34, 2, s52
	s_waitcnt vmcnt(0)

; #define LAS __attribute__((address_space(3)))
; DI void load_lut(float* lut, const float* glut, int col, int lane) {
;     ...
;     for (int k = 0; k < 8; ++k) t[k] = *(const f32x4*)(glut + (size_t)col * 2048 + k * 256 + lane * 4);
; #pragma unroll
;     for (int k = 0; k < 8; ++k) *(f32x4*)(lut + k * 256 + lane * 4) = t[k];
;     __builtin_amdgcn_fence(__ATOMIC_ACQ_REL, "wavefront");
;     __builtin_amdgcn_wave_barrier();
; }
; DI void attn_job(const Args& a, unsigned char* wsh, LAS unsigned char* wl, int type, int b, int qt, int hd, const int tid) {
;     const int lane = tid & 63, r = lane & 31, h = lane >> 5;
;     const bf16_t* prm = (const bf16_t*)(a.ws + WS_R1);
;     const bf16_t* prt = prm + (size_t)MTOK * RM_LD;
;     const float* glut = (const float*)(a.ws + WS_LUT);
;     const unsigned* mask = (const unsigned*)(a.ws + WS_MASK);
;     const float* kmean = (const float*)(a.ws + WS_KMEAN);
;     bf16_t* oabc = (bf16_t*)(a.ws + WS_OABC);
;     float* lut = (float*)(wsh + 8192);
;     const int t0 = qt * 32, tok0 = b * SEQ;
;     const int d00 = t0 + r - 8 * h, h8 = 8 * h;
;     const unsigned* maskrow = mask + (size_t)(tok0 + t0 + r) * 64;
;     AttnCtx c; c.wl = wl; c.lut = lut; c.krs = 1;
; #pragma unroll
;     for (int j = 0; j < 4; ++j) {
;         const int rk = 8 * j + (lane >> 3), ck = (lane & 7) ^ ((rk >> 1) & 7);
;         c.koff[j] = (unsigned)(pi_row(rk) * RM_LD + ck * 8) * 2u;
;         const int rv = 16 * j + (lane >> 2), cv = (lane & 3) ^ ((rv >> 2) & 3);
;         c.voff[j] = (unsigned)(rv * MTOK + cv * 8) * 2u;
;         c.kfo[j] = r * 128 + (((2 * j + h) ^ ((r >> 1) & 7)) * 16);
;     }
; #pragma unroll
;     for (int mt = 0; mt < 2; ++mt)
; #pragma unroll
;         for (int s = 0; s < 2; ++s) c.vfo[mt][s] = (32 * mt + r) * 64 + (((2 * s + h) ^ ((r >> 2) & 3)) * 16);
;     AttnSt st; st.m = NEGF; st.l = 0.f;
; #pragma unroll
;     for (int i = 0; i < 16; ++i) { st.o0[i] = 0.f; st.o1[i] = 0.f; }
;     const int ng = (type == 1) ? 2 : 1;
;     int ocol = 0;
;     for (int g = 0; g < ng; ++g) {
;         int qcol, kcol, vrow, bcol;
;         if (type == 0) { qcol = C_AQ + hd * 64; kcol = C_AK; vrow = R_AV; bcol = hd; ocol = hd * 64; }
;         else if (type == 1) { qcol = C_BQ + (g * 4 + hd) * 64; kcol = C_BK + hd * 64; vrow = R_BV + hd * 64; bcol = 6 + g * 4 + hd; ocol = 384 + hd * 64; }
.LBB0_300:
	s_add_i32 s2, s1, s8
	s_lshl_b32 s2, s2, 11
	v_lshl_add_u64 v[50:51], s[2:3], 2, v[130:131]
	v_add_co_u32_e32 v62, vcc, s94, v50
	s_nop 1
	v_addc_co_u32_e32 v63, vcc, 0, v51, vcc
	global_load_dwordx4 v[2:5], v[50:51], off
	global_load_dwordx4 v[6:9], v[50:51], off offset:1024
	global_load_dwordx4 v[10:13], v[50:51], off offset:2048
	global_load_dwordx4 v[14:17], v[50:51], off offset:3072
	s_nop 0
	global_load_dwordx4 v[50:53], v[62:63], off
	global_load_dwordx4 v[54:57], v[62:63], off offset:1024
	global_load_dwordx4 v[58:61], v[62:63], off offset:2048
	s_nop 0
	global_load_dwordx4 v[62:65], v[62:63], off offset:3072
	s_xor_b64 s[4:5], s[6:7], -1
	s_and_b64 s[6:7], s[6:7], exec
	s_cselect_b32 s2, 0xffffff80, s73
	s_add_i32 s2, s2, s60
	s_max_i32 s6, s2, 0
	s_lshr_b32 s66, s6, 5
	s_cmp_gt_i32 s66, s57
	s_cbranch_scc1 .Lnoh_C
	s_add_i32 s2, s8, s0
	s_lshl_b32 s2, s2, 7
	s_mul_i32 s7, s6, 0x1600
	v_lshl_add_u64 v[82:83], v[146:147], 0, s[2:3]
	s_mul_hi_u32 s2, s6, 0x1600
	s_add_u32 s8, s63, s7
	s_addc_u32 s9, s64, s2
	global_load_dwordx4 v[66:69], v[82:83], off offset:2144
	global_load_dwordx4 v[70:73], v[82:83], off offset:2112
	global_load_dwordx4 v[74:77], v[82:83], off offset:2080
	global_load_dwordx4 v[78:81], v[82:83], off offset:2048
	v_lshl_add_u64 v[82:83], s[8:9], 0, v[116:117]
	s_mov_b32 m0, s49
	v_lshl_add_u64 v[82:83], v[82:83], 0, s[20:21]
	global_load_lds_dwordx4 v[82:83], off
	v_lshl_add_u64 v[82:83], s[8:9], 0, v[118:119]
	s_add_i32 s2, s49, 0x400
	v_lshl_add_u64 v[82:83], v[82:83], 0, s[20:21]
	s_mov_b32 m0, s2
	s_add_i32 s67, s49, 0x800
	global_load_lds_dwordx4 v[82:83], off
	v_lshl_add_u64 v[82:83], s[8:9], 0, v[122:123]
	v_lshl_add_u64 v[82:83], v[82:83], 0, s[20:21]
	s_mov_b32 m0, s67
	s_lshl_b32 s7, s6, 1
	global_load_lds_dwordx4 v[82:83], off
	v_lshl_add_u64 v[82:83], s[8:9], 0, v[126:127]
	s_add_u32 s8, s61, s7
	v_lshl_add_u64 v[82:83], v[82:83], 0, s[20:21]
	s_mov_b32 m0, s53
	s_addc_u32 s9, s62, 0
	s_add_i32 s68, s49, 0x1000
	global_load_lds_dwordx4 v[82:83], off
	v_lshl_add_u64 v[82:83], s[8:9], 0, v[114:115]
	s_mov_b32 m0, s68
	s_add_i32 s69, s49, 0x1800
	global_load_lds_dwordx4 v[82:83], off
	v_lshl_add_u64 v[82:83], s[8:9], 0, v[120:121]
	s_mov_b32 m0, s54
	s_nop 0
	global_load_lds_dwordx4 v[82:83], off
	v_lshl_add_u64 v[82:83], s[8:9], 0, v[124:125]
	s_mov_b32 m0, s69
	s_nop 0
	global_load_lds_dwordx4 v[82:83], off
	v_lshl_add_u64 v[82:83], s[8:9], 0, v[128:129]
	s_mov_b32 m0, s55
	s_nop 0
	global_load_lds_dwordx4 v[82:83], off
.Lnoh_C:
	s_waitcnt vmcnt(0)
	ds_write_b128 v143, v[2:5] offset:8192
	s_waitcnt vmcnt(6)
	ds_write_b128 v143, v[6:9] offset:9216
	s_waitcnt vmcnt(5)
	ds_write_b128 v143, v[10:13] offset:10240
	s_waitcnt vmcnt(4)
	ds_write_b128 v143, v[14:17] offset:11264
	s_waitcnt vmcnt(3)
	ds_write_b128 v143, v[50:53] offset:12288
	s_waitcnt vmcnt(2)
	ds_write_b128 v143, v[54:57] offset:13312
	s_waitcnt vmcnt(1)
	ds_write_b128 v143, v[58:61] offset:14336
	s_waitcnt vmcnt(0)
	ds_write_b128 v143, v[62:65] offset:15360
	s_cmp_gt_i32 s66, s57
	s_cbranch_scc1 .LBB0_315
	v_subrev_u32_e32 v170, s6, v167
	v_subrev_u32_e32 v2, s6, v166
	v_lshl_add_u32 v169, v2, 2, s51
	v_subrev_u32_e32 v2, s6, v168
	v_lshl_add_u32 v171, v2, 2, s52
	s_waitcnt vmcnt(0)

; #define LAS __attribute__((address_space(3)))
; DI void load_lut(float* lut, const float* glut, int col, int lane) {
;     ...
;     for (int k = 0; k < 8; ++k) t[k] = *(const f32x4*)(glut + (size_t)col * 2048 + k * 256 + lane * 4);
; #pragma unroll
;     for (int k = 0; k < 8; ++k) *(f32x4*)(lut + k * 256 + lane * 4) = t[k];
;     __builtin_amdgcn_fence(__ATOMIC_ACQ_REL, "wavefront");
;     __builtin_amdgcn_wave_barrier();
; }
; DI void attn_job(const Args& a, unsigned char* wsh, LAS unsigned char* wl, int type, int b, int qt, int hd, const int tid) {
;     const int lane = tid & 63, r = lane & 31, h = lane >> 5;
;     const bf16_t* prm = (const bf16_t*)(a.ws + WS_R1);
;     const bf16_t* prt = prm + (size_t)MTOK * RM_LD;
;     const float* glut = (const float*)(a.ws + WS_LUT);
;     const unsigned* mask = (const unsigned*)(a.ws + WS_MASK);
;     const float* kmean = (const float*)(a.ws + WS_KMEAN);
;     bf16_t* oabc = (bf16_t*)(a.ws + WS_OABC);
;     float* lut = (float*)(wsh + 8192);
;     const int t0 = qt * 32, tok0 = b * SEQ;
;     const int d00 = t0 + r - 8 * h, h8 = 8 * h;
;     const unsigned* maskrow = mask + (size_t)(tok0 + t0 + r) * 64;
;     AttnCtx c; c.wl = wl; c.lut = lut; c.krs = 1;
; #pragma unroll
;     for (int j = 0; j < 4; ++j) {
;         const int rk = 8 * j + (lane >> 3), ck = (lane & 7) ^ ((rk >> 1) & 7);
;         c.koff[j] = (unsigned)(pi_row(rk) * RM_LD + ck * 8) * 2u;
;         const int rv = 16 * j + (lane >> 2), cv = (lane & 3) ^ ((rv >> 2) & 3);
;         c.voff[j] = (unsigned)(rv * MTOK + cv * 8) * 2u;
;         c.kfo[j] = r * 128 + (((2 * j + h) ^ ((r >> 1) & 7)) * 16);
;     }
; #pragma unroll
;     for (int mt = 0; mt < 2; ++mt)
; #pragma unroll
;         for (int s = 0; s < 2; ++s) c.vfo[mt][s] = (32 * mt + r) * 64 + (((2 * s + h) ^ ((r >> 2) & 3)) * 16);
;     AttnSt st; st.m = NEGF; st.l = 0.f;
; #pragma unroll
;     for (int i = 0; i < 16; ++i) { st.o0[i] = 0.f; st.o1[i] = 0.f; }
;     const int ng = (type == 1) ? 2 : 1;
;     int ocol = 0;
;     for (int g = 0; g < ng; ++g) {
;         int qcol, kcol, vrow, bcol;
;         if (type == 0) { qcol = C_AQ + hd * 64; kcol = C_AK; vrow = R_AV; bcol = hd; ocol = hd * 64; }
;         else if (type == 1) { qcol = C_BQ + (g * 4 + hd) * 64; kcol = C_BK + hd * 64; vrow = R_BV + hd * 64; bcol = 6 + g * 4 + hd; ocol = 384 + hd * 64; }
.LBB0_319:
	s_and_b64 vcc, exec, s[0:1]
	s_cbranch_vccz .LBB0_269
	s_lshl_b32 s8, s57, 5
	s_lshl_b32 s4, s56, 11
	s_add_i32 s60, s8, s4
	v_or_b32_e32 v98, s60, v135
	s_movk_i32 s0, 0x1600
	v_mad_i64_i32 v[94:95], s[0:1], v98, s0, v[132:133]
	s_ashr_i32 s5, s4, 31
	v_readlane_b32 s6, v254, 55
	s_mul_hi_i32 s1, s4, 0x1600
	v_readlane_b32 s7, v254, 56
	s_add_u32 s0, s6, s59
	s_addc_u32 s1, s7, s1
	s_lshl_b64 s[4:5], s[4:5], 1
	v_readlane_b32 s6, v251, 21
	v_readlane_b32 s7, v251, 22
	s_add_u32 s4, s6, s4
	s_addc_u32 s5, s7, s5
	s_lshl_b32 s2, s58, 13
	v_lshl_add_u64 v[96:97], v[130:131], 0, s[2:3]
	v_add_co_u32_e32 v30, vcc, s94, v96
	s_nop 1
	v_addc_co_u32_e32 v31, vcc, 0, v97, vcc
	global_load_dwordx4 v[2:5], v[96:97], off
	global_load_dwordx4 v[6:9], v[96:97], off offset:1024
	global_load_dwordx4 v[10:13], v[96:97], off offset:2048
	global_load_dwordx4 v[14:17], v[96:97], off offset:3072
	global_load_dwordx4 v[18:21], v[30:31], off
	global_load_dwordx4 v[22:25], v[30:31], off offset:1024
	global_load_dwordx4 v[26:29], v[30:31], off offset:2048
	s_nop 0
	global_load_dwordx4 v[30:33], v[30:31], off offset:3072
	s_lshl_b32 s6, s58, 6
	v_ashrrev_i32_e32 v99, 31, v98
	s_cmp_lt_i32 s57, 0
	v_add_u32_e32 v104, s8, v161
	v_mov_b32_e32 v102, 0
	s_mov_b64 s[64:65], 0x300
	s_cbranch_scc1 .Lnoh_A
	s_lshl_b32 s2, s6, 1
	v_lshl_add_u64 v[38:39], s[0:1], 0, v[116:117]
	s_mov_b32 m0, s49
	v_lshl_add_u64 v[36:37], v[94:95], 0, s[2:3]
	v_lshl_add_u64 v[38:39], v[38:39], 0, s[64:65]
	global_load_dwordx4 v[50:53], v[36:37], off offset:96
	global_load_dwordx4 v[54:57], v[36:37], off offset:64
	global_load_dwordx4 v[58:61], v[36:37], off offset:32
	s_add_i32 s7, s49, 0x400
	global_load_lds_dwordx4 v[38:39], off
	v_lshl_add_u64 v[38:39], s[0:1], 0, v[118:119]
	v_lshl_add_u64 v[38:39], v[38:39], 0, s[64:65]
	s_mov_b32 m0, s7
	s_add_i32 s9, s49, 0x800
	global_load_lds_dwordx4 v[38:39], off
	v_lshl_add_u64 v[38:39], s[0:1], 0, v[122:123]
	v_readlane_b32 s46, v251, 27
	v_lshl_add_u64 v[38:39], v[38:39], 0, s[64:65]
	s_mov_b32 m0, s9
	v_lshlrev_b64 v[34:35], 8, v[98:99]
	v_readlane_b32 s47, v251, 28
	global_load_lds_dwordx4 v[38:39], off
	v_lshl_add_u64 v[38:39], s[0:1], 0, v[126:127]
	v_lshl_add_u64 v[34:35], s[46:47], 0, v[34:35]
	v_lshl_add_u64 v[38:39], v[38:39], 0, s[64:65]
	s_mov_b32 m0, s53
	s_add_i32 s46, s49, 0x1000
	global_load_lds_dwordx4 v[38:39], off
	v_lshl_add_u64 v[38:39], s[4:5], 0, v[114:115]
	s_mov_b32 m0, s46
	s_add_i32 s47, s49, 0x1800
	global_load_lds_dwordx4 v[38:39], off
	v_lshl_add_u64 v[38:39], s[4:5], 0, v[120:121]
	s_mov_b32 m0, s54
	s_nop 0
	global_load_lds_dwordx4 v[38:39], off
	v_lshl_add_u64 v[38:39], s[4:5], 0, v[124:125]
	s_mov_b32 m0, s47
	s_nop 0
	global_load_lds_dwordx4 v[38:39], off
	global_load_dwordx4 v[62:65], v[36:37], off
	global_load_dwordx4 v[198:201], v[34:35], off
	v_lshl_add_u64 v[38:39], s[4:5], 0, v[128:129]
	s_mov_b32 m0, s55
	s_nop 0
	global_load_lds_dwordx4 v[38:39], off
.Lnoh_A:
	s_waitcnt vmcnt(0)
	ds_write_b128 v143, v[2:5] offset:8192
	ds_write_b128 v143, v[6:9] offset:9216
	ds_write_b128 v143, v[10:13] offset:10240
	ds_write_b128 v143, v[14:17] offset:11264
	ds_write_b128 v143, v[18:21] offset:12288
	ds_write_b128 v143, v[22:25] offset:13312
	ds_write_b128 v143, v[26:29] offset:14336
	ds_write_b128 v143, v[30:33] offset:15360
	v_mov_b32_e32 v17, 0
	v_mov_b32_e32 v16, 0
	v_mov_b32_e32 v15, 0
	v_mov_b32_e32 v14, 0
	v_mov_b32_e32 v13, 0
	v_mov_b32_e32 v12, 0
	v_mov_b32_e32 v11, 0
	v_mov_b32_e32 v10, 0
	v_mov_b32_e32 v9, 0
	v_mov_b32_e32 v8, 0
	v_mov_b32_e32 v7, 0
	v_mov_b32_e32 v6, 0
	v_mov_b32_e32 v5, 0
	v_mov_b32_e32 v4, 0
	v_mov_b32_e32 v3, 0
	v_mov_b32_e32 v2, 0
	v_mov_b32_e32 v33, 0
	v_mov_b32_e32 v32, 0
	v_mov_b32_e32 v31, 0
	v_mov_b32_e32 v30, 0
	v_mov_b32_e32 v29, 0
	v_mov_b32_e32 v28, 0
	v_mov_b32_e32 v27, 0
	v_mov_b32_e32 v26, 0
	v_mov_b32_e32 v25, 0
	v_mov_b32_e32 v24, 0
	v_mov_b32_e32 v23, 0
	v_mov_b32_e32 v22, 0
	v_mov_b32_e32 v21, 0
	v_mov_b32_e32 v20, 0
	v_mov_b32_e32 v19, 0
	v_mov_b32_e32 v18, 0
	s_cmp_lt_i32 s57, 0
	s_cbranch_scc1 .LBB0_329
	v_mov_b32_e32 v14, v1
	v_mov_b32_e32 v15, v1
	v_add_u32_e32 v2, s60, v135
	v_ashrrev_i32_e32 v3, 31, v2
	v_readlane_b32 s60, v253, 63
	v_lshlrev_b64 v[2:3], 8, v[2:3]
	v_readlane_b32 s61, v254, 0
	v_mov_b32_e32 v0, v1
	v_mov_b32_e32 v4, v1
	v_lshl_add_u64 v[100:101], s[60:61], 0, v[2:3]
	v_mov_b32_e32 v2, v1
	v_mov_b32_e32 v3, v1
	v_mov_b32_e32 v5, v1
	v_mov_b32_e32 v6, v1
	v_mov_b32_e32 v7, v1
	v_mov_b32_e32 v8, v1
	v_mov_b32_e32 v9, v1
	v_mov_b32_e32 v10, v1
	v_mov_b32_e32 v11, v1
	v_mov_b32_e32 v12, v1
	v_mov_b32_e32 v13, v1
	v_mov_b64_e32 v[32:33], v[14:15]
	v_mov_b64_e32 v[30:31], v[12:13]
	v_mov_b64_e32 v[28:29], v[10:11]
	v_mov_b64_e32 v[26:27], v[8:9]
	v_mov_b64_e32 v[24:25], v[6:7]
	v_mov_b64_e32 v[22:23], v[4:5]
	v_mov_b64_e32 v[20:21], v[2:3]
	v_mov_b64_e32 v[18:19], v[0:1]
	v_mov_b64_e32 v[16:17], v[14:15]
	s_add_i32 s59, s57, 1
	v_lshl_add_u32 v103, v104, 2, s51
	s_mov_b32 s60, 0
	v_mov_b32_e32 v105, 0xf149f2ca
	v_mov_b32_e32 v102, 0
	s_mov_b32 s2, 32
	v_mov_b64_e32 v[14:15], v[12:13]
	v_mov_b64_e32 v[12:13], v[10:11]
	v_mov_b64_e32 v[10:11], v[8:9]
	v_mov_b64_e32 v[8:9], v[6:7]
	v_mov_b64_e32 v[6:7], v[4:5]
	v_mov_b64_e32 v[4:5], v[2:3]
	v_mov_b64_e32 v[2:3], v[0:1]
	s_waitcnt vmcnt(0)
	v_mov_b32_e32 v106, v198
